# up-GEMM epilogue hand-written: DPP fused into fmac, masked edge weights, prefetched second weight set
# speedup vs baseline: 1.0166x; 1.0166x over previous
.LBB0_186:
	v_readlane_b32 s76, v252, 59
	v_readlane_b32 s77, v252, 60
	v_cmp_eq_u32_e64 s[38:39], 0, v208
	v_cmp_eq_u32_e64 s[40:41], 15, v208
	v_readlane_b32 s4, v253, 18
	v_readlane_b32 s5, v253, 34
	v_readlane_b32 s8, v254, 59
	v_readlane_b32 s9, v254, 60
	v_readlane_b32 s14, v254, 55
	v_readlane_b32 s15, v254, 56
	v_readlane_b32 s42, v254, 61
	v_readlane_b32 s43, v254, 62
	v_readlane_b32 s94, v254, 57
	v_readlane_b32 s95, v254, 58
	s_lshl_b32 s6, s73, 9
	s_lshl_b32 s7, s4, 5
	s_add_i32 s7, s7, 0x20000
	v_lshl_add_u32 v242, v209, 3, s5
	v_mul_u32_u24_e32 v217, 0x2c00, v208
	v_lshl_add_u32 v196, v242, 2, s6
	v_lshl_add_u32 v197, v242, 2, s7
	v_lshl_add_u32 v217, v242, 1, v217
	s_add_u32 s26, s8, 0
	s_addc_u32 s27, s9, 0
	global_load_dwordx4 v[118:121], v196, s[26:27] offset:0
	s_add_u32 s26, s8, 22528
	s_addc_u32 s27, s9, 0
	global_load_dwordx4 v[122:125], v196, s[26:27] offset:0
	s_add_u32 s26, s14, 0
	s_addc_u32 s27, s15, 0
	global_load_dwordx4 v[126:129], v196, s[26:27] offset:0
	s_add_u32 s26, s14, 22528
	s_addc_u32 s27, s15, 0
	global_load_dwordx4 v[130:133], v196, s[26:27] offset:0
	s_add_u32 s26, s16, 0
	s_addc_u32 s27, s17, 0
	global_load_dwordx4 v[134:137], v196, s[26:27] offset:0
	s_add_u32 s26, s16, 22528
	s_addc_u32 s27, s17, 0
	global_load_dwordx4 v[138:141], v196, s[26:27] offset:0
	s_add_u32 s26, s42, 0
	s_addc_u32 s27, s43, 0
	global_load_dwordx4 v[142:145], v196, s[26:27] offset:0
	s_add_u32 s26, s42, 22528
	s_addc_u32 s27, s43, 0
	global_load_dwordx4 v[150:153], v196, s[26:27] offset:0
	s_lshl_b32 s6, s72, 8
	s_add_i32 s6, s6, s4
	s_mul_i32 s6, s6, 0x2c00
	s_add_u32 s94, s94, s6
	s_addc_u32 s95, s95, 0
	s_lshl_b32 s6, s73, 8
	s_add_u32 s94, s94, s6
	s_addc_u32 s95, s95, 0
	s_mov_b64 exec, s[38:39]
	ds_write_b128 v197, v[158:161] offset:0
	ds_write_b128 v197, v[62:65] offset:16
	ds_write_b128 v197, v[154:157] offset:512
	ds_write_b128 v197, v[58:61] offset:528
	ds_write_b128 v197, v[94:97] offset:4096
	ds_write_b128 v197, v[30:33] offset:4112
	ds_write_b128 v197, v[90:93] offset:4608
	ds_write_b128 v197, v[26:29] offset:4624
	s_mov_b64 exec, s[40:41]
	ds_write_b128 v197, v[102:105] offset:1024
	ds_write_b128 v197, v[38:41] offset:1040
	ds_write_b128 v197, v[98:101] offset:1536
	ds_write_b128 v197, v[34:37] offset:1552
	ds_write_b128 v197, v[66:69] offset:5120
	ds_write_b128 v197, v[2:5] offset:5136
	ds_write_b128 v197, v[70:73] offset:5632
	ds_write_b128 v197, v[6:9] offset:5648
	s_mov_b64 exec, -1
	v_add_u32_e32 v242, 0x800, v197
	v_add_u32_e32 v243, 0xfffffc00, v197
	v_cndmask_b32_e64 v244, v243, v242, s[40:41]
	s_cmp_eq_u32 s4, 0
	s_cselect_b64 vcc, -1, 0
	s_mov_b32 s6, 0xbfb8aa3b
	s_nop 0
	v_cndmask_b32_e32 v216, v244, v242, vcc
	s_cmp_eq_u32 s4, 64
	s_cselect_b64 vcc, -1, 0
	s_nop 1
	v_cndmask_b32_e32 v197, v244, v243, vcc
	s_waitcnt lgkmcnt(0)
	s_barrier
	ds_read_b128 v[188:191], v216 offset:0
	ds_read_b128 v[192:195], v216 offset:512
	s_waitcnt vmcnt(0)
	v_cndmask_b32_e64 v162, 0, v118, s[38:39]
	v_cndmask_b32_e64 v170, 0, v134, s[40:41]
	v_cndmask_b32_e64 v163, 0, v119, s[38:39]
	v_cndmask_b32_e64 v171, 0, v135, s[40:41]
	v_cndmask_b32_e64 v164, 0, v120, s[38:39]
	v_cndmask_b32_e64 v172, 0, v136, s[40:41]
	v_cndmask_b32_e64 v165, 0, v121, s[38:39]
	v_cndmask_b32_e64 v173, 0, v137, s[40:41]
	v_cndmask_b32_e64 v166, 0, v122, s[38:39]
	v_cndmask_b32_e64 v174, 0, v138, s[40:41]
	v_cndmask_b32_e64 v167, 0, v123, s[38:39]
	v_cndmask_b32_e64 v175, 0, v139, s[40:41]
	v_cndmask_b32_e64 v168, 0, v124, s[38:39]
	v_cndmask_b32_e64 v176, 0, v140, s[40:41]
	v_cndmask_b32_e64 v169, 0, v125, s[38:39]
	v_cndmask_b32_e64 v177, 0, v141, s[40:41]
	v_pk_fma_f32 v[212:213], v[126:127], v[158:159], v[142:143]
	v_pk_fma_f32 v[214:215], v[128:129], v[160:161], v[144:145]
	v_pk_fma_f32 v[238:239], v[130:131], v[154:155], v[150:151]
	v_pk_fma_f32 v[240:241], v[132:133], v[156:157], v[152:153]
	v_fmac_f32_dpp v212, v158, v118 row_shr:1 row_mask:0xf bank_mask:0xf
	v_fmac_f32_dpp v213, v159, v119 row_shr:1 row_mask:0xf bank_mask:0xf
	v_fmac_f32_dpp v214, v160, v120 row_shr:1 row_mask:0xf bank_mask:0xf
	v_fmac_f32_dpp v215, v161, v121 row_shr:1 row_mask:0xf bank_mask:0xf
	v_fmac_f32_dpp v238, v154, v122 row_shr:1 row_mask:0xf bank_mask:0xf
	v_fmac_f32_dpp v239, v155, v123 row_shr:1 row_mask:0xf bank_mask:0xf
	v_fmac_f32_dpp v240, v156, v124 row_shr:1 row_mask:0xf bank_mask:0xf
	v_fmac_f32_dpp v241, v157, v125 row_shr:1 row_mask:0xf bank_mask:0xf
	v_fmac_f32_dpp v212, v158, v134 row_shl:1 row_mask:0xf bank_mask:0xf
	v_fmac_f32_dpp v213, v159, v135 row_shl:1 row_mask:0xf bank_mask:0xf
	v_fmac_f32_dpp v214, v160, v136 row_shl:1 row_mask:0xf bank_mask:0xf
	v_fmac_f32_dpp v215, v161, v137 row_shl:1 row_mask:0xf bank_mask:0xf
	v_fmac_f32_dpp v238, v154, v138 row_shl:1 row_mask:0xf bank_mask:0xf
	v_fmac_f32_dpp v239, v155, v139 row_shl:1 row_mask:0xf bank_mask:0xf
	v_fmac_f32_dpp v240, v156, v140 row_shl:1 row_mask:0xf bank_mask:0xf
	v_fmac_f32_dpp v241, v157, v141 row_shl:1 row_mask:0xf bank_mask:0xf
	s_waitcnt lgkmcnt(0)
	s_cmp_eq_u32 s4, 0
	s_cbranch_scc1 .Lupc_1
	v_pk_fma_f32 v[212:213], v[188:189], v[162:163], v[212:213]
	v_pk_fma_f32 v[214:215], v[190:191], v[164:165], v[214:215]
	v_pk_fma_f32 v[238:239], v[192:193], v[166:167], v[238:239]
	v_pk_fma_f32 v[240:241], v[194:195], v[168:169], v[240:241]
.Lupc_1:
	v_fmac_f32_dpp v212, v146, v170 row_ror:15 row_mask:0xf bank_mask:0xf
	v_fmac_f32_dpp v213, v147, v171 row_ror:15 row_mask:0xf bank_mask:0xf
	v_fmac_f32_dpp v214, v148, v172 row_ror:15 row_mask:0xf bank_mask:0xf
	v_fmac_f32_dpp v215, v149, v173 row_ror:15 row_mask:0xf bank_mask:0xf
	v_fmac_f32_dpp v238, v114, v174 row_ror:15 row_mask:0xf bank_mask:0xf
	v_fmac_f32_dpp v239, v115, v175 row_ror:15 row_mask:0xf bank_mask:0xf
	v_fmac_f32_dpp v240, v116, v176 row_ror:15 row_mask:0xf bank_mask:0xf
	v_fmac_f32_dpp v241, v117, v177 row_ror:15 row_mask:0xf bank_mask:0xf
	s_cmp_lg_u32 s4, 0
	s_cbranch_scc1 .Lupc_2
	s_mov_b64 exec, s[38:39]
	s_lshl_b32 s7, s72, 1
	s_mul_i32 s7, s7, 0xb000
	v_readlane_b32 s26, v255, 0
	v_readlane_b32 s27, v255, 1
	s_add_u32 s26, s26, s7
	s_addc_u32 s27, s27, 0
	global_store_dwordx4 v196, v[158:161], s[26:27] offset:0
	s_add_u32 s26, s26, 22528
	s_addc_u32 s27, s27, 0
	global_store_dwordx4 v196, v[154:157], s[26:27] offset:0
	v_readlane_b32 s26, v255, 15
	v_readlane_b32 s27, v255, 16
	s_add_u32 s26, s26, s7
	s_addc_u32 s27, s27, 0
	global_store_dwordx4 v196, v[212:215], s[26:27] offset:0
	s_add_u32 s26, s26, 22528
	s_addc_u32 s27, s27, 0
	global_store_dwordx4 v196, v[238:241], s[26:27] offset:0
	s_mov_b64 exec, -1
.Lupc_2:
	v_pk_mul_f32 v[242:243], v[238:239], s[6:7] op_sel_hi:[1,0]
	v_pk_mul_f32 v[244:245], v[240:241], s[6:7] op_sel_hi:[1,0]
	v_exp_f32_e32 v242, v242
	v_exp_f32_e32 v243, v243
	v_exp_f32_e32 v244, v244
	v_exp_f32_e32 v245, v245
	v_add_f32_e32 v242, 1.0, v242
	v_add_f32_e32 v243, 1.0, v243
	v_add_f32_e32 v244, 1.0, v244
	v_add_f32_e32 v245, 1.0, v245
	v_rcp_f32_e32 v242, v242
	v_rcp_f32_e32 v243, v243
	v_rcp_f32_e32 v244, v244
	v_rcp_f32_e32 v245, v245
	s_nop 0
	v_pk_mul_f32 v[242:243], v[238:239], v[242:243]
	v_pk_mul_f32 v[244:245], v[240:241], v[244:245]
	v_pk_mul_f32 v[242:243], v[212:213], v[242:243]
	v_pk_mul_f32 v[244:245], v[214:215], v[244:245]
	v_cvt_pk_bf16_f32 v246, v242, v243
	v_cvt_pk_bf16_f32 v247, v244, v245
	global_store_dwordx2 v217, v[246:247], s[94:95] offset:0
	v_pk_fma_f32 v[212:213], v[126:127], v[146:147], v[142:143]
	v_pk_fma_f32 v[214:215], v[128:129], v[148:149], v[144:145]
	v_pk_fma_f32 v[238:239], v[130:131], v[114:115], v[150:151]
	v_pk_fma_f32 v[240:241], v[132:133], v[116:117], v[152:153]
	v_fmac_f32_dpp v212, v146, v118 row_shr:1 row_mask:0xf bank_mask:0xf
	v_fmac_f32_dpp v213, v147, v119 row_shr:1 row_mask:0xf bank_mask:0xf
	v_fmac_f32_dpp v214, v148, v120 row_shr:1 row_mask:0xf bank_mask:0xf
	v_fmac_f32_dpp v215, v149, v121 row_shr:1 row_mask:0xf bank_mask:0xf
	v_fmac_f32_dpp v238, v114, v122 row_shr:1 row_mask:0xf bank_mask:0xf
	v_fmac_f32_dpp v239, v115, v123 row_shr:1 row_mask:0xf bank_mask:0xf
	v_fmac_f32_dpp v240, v116, v124 row_shr:1 row_mask:0xf bank_mask:0xf
	v_fmac_f32_dpp v241, v117, v125 row_shr:1 row_mask:0xf bank_mask:0xf
	v_fmac_f32_dpp v212, v146, v134 row_shl:1 row_mask:0xf bank_mask:0xf
	v_fmac_f32_dpp v213, v147, v135 row_shl:1 row_mask:0xf bank_mask:0xf
	v_fmac_f32_dpp v214, v148, v136 row_shl:1 row_mask:0xf bank_mask:0xf
	v_fmac_f32_dpp v215, v149, v137 row_shl:1 row_mask:0xf bank_mask:0xf
	v_fmac_f32_dpp v238, v114, v138 row_shl:1 row_mask:0xf bank_mask:0xf
	v_fmac_f32_dpp v239, v115, v139 row_shl:1 row_mask:0xf bank_mask:0xf
	v_fmac_f32_dpp v240, v116, v140 row_shl:1 row_mask:0xf bank_mask:0xf
	v_fmac_f32_dpp v241, v117, v141 row_shl:1 row_mask:0xf bank_mask:0xf
	v_fmac_f32_dpp v212, v158, v162 row_ror:1 row_mask:0xf bank_mask:0xf
	v_fmac_f32_dpp v213, v159, v163 row_ror:1 row_mask:0xf bank_mask:0xf
	v_fmac_f32_dpp v214, v160, v164 row_ror:1 row_mask:0xf bank_mask:0xf
	v_fmac_f32_dpp v215, v161, v165 row_ror:1 row_mask:0xf bank_mask:0xf
	v_fmac_f32_dpp v238, v154, v166 row_ror:1 row_mask:0xf bank_mask:0xf
	v_fmac_f32_dpp v239, v155, v167 row_ror:1 row_mask:0xf bank_mask:0xf
	v_fmac_f32_dpp v240, v156, v168 row_ror:1 row_mask:0xf bank_mask:0xf
	v_fmac_f32_dpp v241, v157, v169 row_ror:1 row_mask:0xf bank_mask:0xf
	v_fmac_f32_dpp v212, v110, v170 row_ror:15 row_mask:0xf bank_mask:0xf
	v_fmac_f32_dpp v213, v111, v171 row_ror:15 row_mask:0xf bank_mask:0xf
	v_fmac_f32_dpp v214, v112, v172 row_ror:15 row_mask:0xf bank_mask:0xf
	v_fmac_f32_dpp v215, v113, v173 row_ror:15 row_mask:0xf bank_mask:0xf
	v_fmac_f32_dpp v238, v106, v174 row_ror:15 row_mask:0xf bank_mask:0xf
	v_fmac_f32_dpp v239, v107, v175 row_ror:15 row_mask:0xf bank_mask:0xf
	v_fmac_f32_dpp v240, v108, v176 row_ror:15 row_mask:0xf bank_mask:0xf
	v_fmac_f32_dpp v241, v109, v177 row_ror:15 row_mask:0xf bank_mask:0xf
	v_pk_mul_f32 v[242:243], v[238:239], s[6:7] op_sel_hi:[1,0]
	v_pk_mul_f32 v[244:245], v[240:241], s[6:7] op_sel_hi:[1,0]
	v_exp_f32_e32 v242, v242
	v_exp_f32_e32 v243, v243
	v_exp_f32_e32 v244, v244
	v_exp_f32_e32 v245, v245
	v_add_f32_e32 v242, 1.0, v242
	v_add_f32_e32 v243, 1.0, v243
	v_add_f32_e32 v244, 1.0, v244
	v_add_f32_e32 v245, 1.0, v245
	v_rcp_f32_e32 v242, v242
	v_rcp_f32_e32 v243, v243
	v_rcp_f32_e32 v244, v244
	v_rcp_f32_e32 v245, v245
	s_nop 0
	v_pk_mul_f32 v[242:243], v[238:239], v[242:243]
	v_pk_mul_f32 v[244:245], v[240:241], v[244:245]
	v_pk_mul_f32 v[242:243], v[212:213], v[242:243]
	v_pk_mul_f32 v[244:245], v[214:215], v[244:245]
	v_cvt_pk_bf16_f32 v246, v242, v243
	v_cvt_pk_bf16_f32 v247, v244, v245
	s_add_u32 s26, s94, 0x2c000
	s_addc_u32 s27, s95, 0
	global_store_dwordx2 v217, v[246:247], s[26:27] offset:0
	v_pk_fma_f32 v[212:213], v[126:127], v[110:111], v[142:143]
	v_pk_fma_f32 v[214:215], v[128:129], v[112:113], v[144:145]
	v_pk_fma_f32 v[238:239], v[130:131], v[106:107], v[150:151]
	v_pk_fma_f32 v[240:241], v[132:133], v[108:109], v[152:153]
	v_fmac_f32_dpp v212, v110, v118 row_shr:1 row_mask:0xf bank_mask:0xf
	v_fmac_f32_dpp v213, v111, v119 row_shr:1 row_mask:0xf bank_mask:0xf
	v_fmac_f32_dpp v214, v112, v120 row_shr:1 row_mask:0xf bank_mask:0xf
	v_fmac_f32_dpp v215, v113, v121 row_shr:1 row_mask:0xf bank_mask:0xf
	v_fmac_f32_dpp v238, v106, v122 row_shr:1 row_mask:0xf bank_mask:0xf
	v_fmac_f32_dpp v239, v107, v123 row_shr:1 row_mask:0xf bank_mask:0xf
	v_fmac_f32_dpp v240, v108, v124 row_shr:1 row_mask:0xf bank_mask:0xf
	v_fmac_f32_dpp v241, v109, v125 row_shr:1 row_mask:0xf bank_mask:0xf
	v_fmac_f32_dpp v212, v110, v134 row_shl:1 row_mask:0xf bank_mask:0xf
	v_fmac_f32_dpp v213, v111, v135 row_shl:1 row_mask:0xf bank_mask:0xf
	v_fmac_f32_dpp v214, v112, v136 row_shl:1 row_mask:0xf bank_mask:0xf
	v_fmac_f32_dpp v215, v113, v137 row_shl:1 row_mask:0xf bank_mask:0xf
	v_fmac_f32_dpp v238, v106, v138 row_shl:1 row_mask:0xf bank_mask:0xf
	v_fmac_f32_dpp v239, v107, v139 row_shl:1 row_mask:0xf bank_mask:0xf
	v_fmac_f32_dpp v240, v108, v140 row_shl:1 row_mask:0xf bank_mask:0xf
	v_fmac_f32_dpp v241, v109, v141 row_shl:1 row_mask:0xf bank_mask:0xf
	v_fmac_f32_dpp v212, v146, v162 row_ror:1 row_mask:0xf bank_mask:0xf
	v_fmac_f32_dpp v213, v147, v163 row_ror:1 row_mask:0xf bank_mask:0xf
	v_fmac_f32_dpp v214, v148, v164 row_ror:1 row_mask:0xf bank_mask:0xf
	v_fmac_f32_dpp v215, v149, v165 row_ror:1 row_mask:0xf bank_mask:0xf
	v_fmac_f32_dpp v238, v114, v166 row_ror:1 row_mask:0xf bank_mask:0xf
	v_fmac_f32_dpp v239, v115, v167 row_ror:1 row_mask:0xf bank_mask:0xf
	v_fmac_f32_dpp v240, v116, v168 row_ror:1 row_mask:0xf bank_mask:0xf
	v_fmac_f32_dpp v241, v117, v169 row_ror:1 row_mask:0xf bank_mask:0xf
	v_fmac_f32_dpp v212, v102, v170 row_ror:15 row_mask:0xf bank_mask:0xf
	v_fmac_f32_dpp v213, v103, v171 row_ror:15 row_mask:0xf bank_mask:0xf
	v_fmac_f32_dpp v214, v104, v172 row_ror:15 row_mask:0xf bank_mask:0xf
	v_fmac_f32_dpp v215, v105, v173 row_ror:15 row_mask:0xf bank_mask:0xf
	v_fmac_f32_dpp v238, v98, v174 row_ror:15 row_mask:0xf bank_mask:0xf
	v_fmac_f32_dpp v239, v99, v175 row_ror:15 row_mask:0xf bank_mask:0xf
	v_fmac_f32_dpp v240, v100, v176 row_ror:15 row_mask:0xf bank_mask:0xf
	v_fmac_f32_dpp v241, v101, v177 row_ror:15 row_mask:0xf bank_mask:0xf
	v_pk_mul_f32 v[242:243], v[238:239], s[6:7] op_sel_hi:[1,0]
	v_pk_mul_f32 v[244:245], v[240:241], s[6:7] op_sel_hi:[1,0]
	v_exp_f32_e32 v242, v242
	v_exp_f32_e32 v243, v243
	v_exp_f32_e32 v244, v244
	v_exp_f32_e32 v245, v245
	v_add_f32_e32 v242, 1.0, v242
	v_add_f32_e32 v243, 1.0, v243
	v_add_f32_e32 v244, 1.0, v244
	v_add_f32_e32 v245, 1.0, v245
	v_rcp_f32_e32 v242, v242
	v_rcp_f32_e32 v243, v243
	v_rcp_f32_e32 v244, v244
	v_rcp_f32_e32 v245, v245
	s_nop 0
	v_pk_mul_f32 v[242:243], v[238:239], v[242:243]
	v_pk_mul_f32 v[244:245], v[240:241], v[244:245]
	v_pk_mul_f32 v[242:243], v[212:213], v[242:243]
	v_pk_mul_f32 v[244:245], v[214:215], v[244:245]
	v_cvt_pk_bf16_f32 v246, v242, v243
	v_cvt_pk_bf16_f32 v247, v244, v245
	s_add_u32 s26, s94, 0x58000
	s_addc_u32 s27, s95, 0
	global_store_dwordx2 v217, v[246:247], s[26:27] offset:0
	v_pk_fma_f32 v[212:213], v[126:127], v[102:103], v[142:143]
	v_pk_fma_f32 v[214:215], v[128:129], v[104:105], v[144:145]
	v_pk_fma_f32 v[238:239], v[130:131], v[98:99], v[150:151]
	v_pk_fma_f32 v[240:241], v[132:133], v[100:101], v[152:153]
	v_fmac_f32_dpp v212, v102, v118 row_shr:1 row_mask:0xf bank_mask:0xf
	v_fmac_f32_dpp v213, v103, v119 row_shr:1 row_mask:0xf bank_mask:0xf
	v_fmac_f32_dpp v214, v104, v120 row_shr:1 row_mask:0xf bank_mask:0xf
	v_fmac_f32_dpp v215, v105, v121 row_shr:1 row_mask:0xf bank_mask:0xf
	v_fmac_f32_dpp v238, v98, v122 row_shr:1 row_mask:0xf bank_mask:0xf
	v_fmac_f32_dpp v239, v99, v123 row_shr:1 row_mask:0xf bank_mask:0xf
	v_fmac_f32_dpp v240, v100, v124 row_shr:1 row_mask:0xf bank_mask:0xf
	v_fmac_f32_dpp v241, v101, v125 row_shr:1 row_mask:0xf bank_mask:0xf
	v_fmac_f32_dpp v212, v102, v134 row_shl:1 row_mask:0xf bank_mask:0xf
	v_fmac_f32_dpp v213, v103, v135 row_shl:1 row_mask:0xf bank_mask:0xf
	v_fmac_f32_dpp v214, v104, v136 row_shl:1 row_mask:0xf bank_mask:0xf
	v_fmac_f32_dpp v215, v105, v137 row_shl:1 row_mask:0xf bank_mask:0xf
	v_fmac_f32_dpp v238, v98, v138 row_shl:1 row_mask:0xf bank_mask:0xf
	v_fmac_f32_dpp v239, v99, v139 row_shl:1 row_mask:0xf bank_mask:0xf
	v_fmac_f32_dpp v240, v100, v140 row_shl:1 row_mask:0xf bank_mask:0xf
	v_fmac_f32_dpp v241, v101, v141 row_shl:1 row_mask:0xf bank_mask:0xf
	v_fmac_f32_dpp v212, v110, v162 row_ror:1 row_mask:0xf bank_mask:0xf
	v_fmac_f32_dpp v213, v111, v163 row_ror:1 row_mask:0xf bank_mask:0xf
	v_fmac_f32_dpp v214, v112, v164 row_ror:1 row_mask:0xf bank_mask:0xf
	v_fmac_f32_dpp v215, v113, v165 row_ror:1 row_mask:0xf bank_mask:0xf
	v_fmac_f32_dpp v238, v106, v166 row_ror:1 row_mask:0xf bank_mask:0xf
	v_fmac_f32_dpp v239, v107, v167 row_ror:1 row_mask:0xf bank_mask:0xf
	v_fmac_f32_dpp v240, v108, v168 row_ror:1 row_mask:0xf bank_mask:0xf
	v_fmac_f32_dpp v241, v109, v169 row_ror:1 row_mask:0xf bank_mask:0xf
	v_pk_fma_f32 v[212:213], v[188:189], v[170:171], v[212:213]
	v_pk_fma_f32 v[214:215], v[190:191], v[172:173], v[214:215]
	v_pk_fma_f32 v[238:239], v[192:193], v[174:175], v[238:239]
	v_pk_fma_f32 v[240:241], v[194:195], v[176:177], v[240:241]
	v_pk_mul_f32 v[242:243], v[238:239], s[6:7] op_sel_hi:[1,0]
	v_pk_mul_f32 v[244:245], v[240:241], s[6:7] op_sel_hi:[1,0]
	v_exp_f32_e32 v242, v242
	v_exp_f32_e32 v243, v243
	v_exp_f32_e32 v244, v244
	v_exp_f32_e32 v245, v245
	v_add_f32_e32 v242, 1.0, v242
	v_add_f32_e32 v243, 1.0, v243
	v_add_f32_e32 v244, 1.0, v244
	v_add_f32_e32 v245, 1.0, v245
	v_rcp_f32_e32 v242, v242
	v_rcp_f32_e32 v243, v243
	v_rcp_f32_e32 v244, v244
	v_rcp_f32_e32 v245, v245
	s_nop 0
	v_pk_mul_f32 v[242:243], v[238:239], v[242:243]
	v_pk_mul_f32 v[244:245], v[240:241], v[244:245]
	v_pk_mul_f32 v[242:243], v[212:213], v[242:243]
	v_pk_mul_f32 v[244:245], v[214:215], v[244:245]
	v_cvt_pk_bf16_f32 v246, v242, v243
	v_cvt_pk_bf16_f32 v247, v244, v245
	s_add_u32 s26, s94, 0x84000
	s_addc_u32 s27, s95, 0
	global_store_dwordx2 v217, v[246:247], s[26:27] offset:0
	s_add_u32 s26, s8, 0
	s_addc_u32 s27, s9, 0
	global_load_dwordx4 v[158:161], v196, s[26:27] offset:16
	s_add_u32 s26, s8, 22528
	s_addc_u32 s27, s9, 0
	global_load_dwordx4 v[154:157], v196, s[26:27] offset:16
	s_add_u32 s26, s14, 0
	s_addc_u32 s27, s15, 0
	global_load_dwordx4 v[146:149], v196, s[26:27] offset:16
	s_add_u32 s26, s14, 22528
	s_addc_u32 s27, s15, 0
	global_load_dwordx4 v[114:117], v196, s[26:27] offset:16
	s_add_u32 s26, s16, 0
	s_addc_u32 s27, s17, 0
	global_load_dwordx4 v[110:113], v196, s[26:27] offset:16
	s_add_u32 s26, s16, 22528
	s_addc_u32 s27, s17, 0
	global_load_dwordx4 v[106:109], v196, s[26:27] offset:16
	s_add_u32 s26, s42, 0
	s_addc_u32 s27, s43, 0
	global_load_dwordx4 v[102:105], v196, s[26:27] offset:16
	s_add_u32 s26, s42, 22528
	s_addc_u32 s27, s43, 0
	global_load_dwordx4 v[98:101], v196, s[26:27] offset:16
	ds_read_b128 v[188:191], v197 offset:4096
	ds_read_b128 v[192:195], v197 offset:4608
	v_pk_fma_f32 v[212:213], v[126:127], v[94:95], v[142:143]
	v_pk_fma_f32 v[214:215], v[128:129], v[96:97], v[144:145]
	v_pk_fma_f32 v[238:239], v[130:131], v[90:91], v[150:151]
	v_pk_fma_f32 v[240:241], v[132:133], v[92:93], v[152:153]
	v_fmac_f32_dpp v212, v94, v118 row_shr:1 row_mask:0xf bank_mask:0xf
	v_fmac_f32_dpp v213, v95, v119 row_shr:1 row_mask:0xf bank_mask:0xf
	v_fmac_f32_dpp v214, v96, v120 row_shr:1 row_mask:0xf bank_mask:0xf
	v_fmac_f32_dpp v215, v97, v121 row_shr:1 row_mask:0xf bank_mask:0xf
	v_fmac_f32_dpp v238, v90, v122 row_shr:1 row_mask:0xf bank_mask:0xf
	v_fmac_f32_dpp v239, v91, v123 row_shr:1 row_mask:0xf bank_mask:0xf
	v_fmac_f32_dpp v240, v92, v124 row_shr:1 row_mask:0xf bank_mask:0xf
	v_fmac_f32_dpp v241, v93, v125 row_shr:1 row_mask:0xf bank_mask:0xf
	v_fmac_f32_dpp v212, v94, v134 row_shl:1 row_mask:0xf bank_mask:0xf
	v_fmac_f32_dpp v213, v95, v135 row_shl:1 row_mask:0xf bank_mask:0xf
	v_fmac_f32_dpp v214, v96, v136 row_shl:1 row_mask:0xf bank_mask:0xf
	v_fmac_f32_dpp v215, v97, v137 row_shl:1 row_mask:0xf bank_mask:0xf
	v_fmac_f32_dpp v238, v90, v138 row_shl:1 row_mask:0xf bank_mask:0xf
	v_fmac_f32_dpp v239, v91, v139 row_shl:1 row_mask:0xf bank_mask:0xf
	v_fmac_f32_dpp v240, v92, v140 row_shl:1 row_mask:0xf bank_mask:0xf
	v_fmac_f32_dpp v241, v93, v141 row_shl:1 row_mask:0xf bank_mask:0xf
	s_waitcnt lgkmcnt(0)
	v_pk_fma_f32 v[212:213], v[188:189], v[162:163], v[212:213]
	v_pk_fma_f32 v[214:215], v[190:191], v[164:165], v[214:215]
	v_pk_fma_f32 v[238:239], v[192:193], v[166:167], v[238:239]
	v_pk_fma_f32 v[240:241], v[194:195], v[168:169], v[240:241]
	v_fmac_f32_dpp v212, v86, v170 row_ror:15 row_mask:0xf bank_mask:0xf
	v_fmac_f32_dpp v213, v87, v171 row_ror:15 row_mask:0xf bank_mask:0xf
	v_fmac_f32_dpp v214, v88, v172 row_ror:15 row_mask:0xf bank_mask:0xf
	v_fmac_f32_dpp v215, v89, v173 row_ror:15 row_mask:0xf bank_mask:0xf
	v_fmac_f32_dpp v238, v82, v174 row_ror:15 row_mask:0xf bank_mask:0xf
	v_fmac_f32_dpp v239, v83, v175 row_ror:15 row_mask:0xf bank_mask:0xf
	v_fmac_f32_dpp v240, v84, v176 row_ror:15 row_mask:0xf bank_mask:0xf
	v_fmac_f32_dpp v241, v85, v177 row_ror:15 row_mask:0xf bank_mask:0xf
	v_pk_mul_f32 v[242:243], v[238:239], s[6:7] op_sel_hi:[1,0]
	v_pk_mul_f32 v[244:245], v[240:241], s[6:7] op_sel_hi:[1,0]
	v_exp_f32_e32 v242, v242
	v_exp_f32_e32 v243, v243
	v_exp_f32_e32 v244, v244
	v_exp_f32_e32 v245, v245
	v_add_f32_e32 v242, 1.0, v242
	v_add_f32_e32 v243, 1.0, v243
	v_add_f32_e32 v244, 1.0, v244
	v_add_f32_e32 v245, 1.0, v245
	v_rcp_f32_e32 v242, v242
	v_rcp_f32_e32 v243, v243
	v_rcp_f32_e32 v244, v244
	v_rcp_f32_e32 v245, v245
	s_nop 0
	v_pk_mul_f32 v[242:243], v[238:239], v[242:243]
	v_pk_mul_f32 v[244:245], v[240:241], v[244:245]
	v_pk_mul_f32 v[242:243], v[212:213], v[242:243]
	v_pk_mul_f32 v[244:245], v[214:215], v[244:245]
	v_cvt_pk_bf16_f32 v246, v242, v243
	v_cvt_pk_bf16_f32 v247, v244, v245
	s_add_u32 s26, s94, 0x160000
	s_addc_u32 s27, s95, 0
	global_store_dwordx2 v217, v[246:247], s[26:27] offset:0
	v_pk_fma_f32 v[212:213], v[126:127], v[86:87], v[142:143]
	v_pk_fma_f32 v[214:215], v[128:129], v[88:89], v[144:145]
	v_pk_fma_f32 v[238:239], v[130:131], v[82:83], v[150:151]
	v_pk_fma_f32 v[240:241], v[132:133], v[84:85], v[152:153]
	v_fmac_f32_dpp v212, v86, v118 row_shr:1 row_mask:0xf bank_mask:0xf
	v_fmac_f32_dpp v213, v87, v119 row_shr:1 row_mask:0xf bank_mask:0xf
	v_fmac_f32_dpp v214, v88, v120 row_shr:1 row_mask:0xf bank_mask:0xf
	v_fmac_f32_dpp v215, v89, v121 row_shr:1 row_mask:0xf bank_mask:0xf
	v_fmac_f32_dpp v238, v82, v122 row_shr:1 row_mask:0xf bank_mask:0xf
	v_fmac_f32_dpp v239, v83, v123 row_shr:1 row_mask:0xf bank_mask:0xf
	v_fmac_f32_dpp v240, v84, v124 row_shr:1 row_mask:0xf bank_mask:0xf
	v_fmac_f32_dpp v241, v85, v125 row_shr:1 row_mask:0xf bank_mask:0xf
	v_fmac_f32_dpp v212, v86, v134 row_shl:1 row_mask:0xf bank_mask:0xf
	v_fmac_f32_dpp v213, v87, v135 row_shl:1 row_mask:0xf bank_mask:0xf
	v_fmac_f32_dpp v214, v88, v136 row_shl:1 row_mask:0xf bank_mask:0xf
	v_fmac_f32_dpp v215, v89, v137 row_shl:1 row_mask:0xf bank_mask:0xf
	v_fmac_f32_dpp v238, v82, v138 row_shl:1 row_mask:0xf bank_mask:0xf
	v_fmac_f32_dpp v239, v83, v139 row_shl:1 row_mask:0xf bank_mask:0xf
	v_fmac_f32_dpp v240, v84, v140 row_shl:1 row_mask:0xf bank_mask:0xf
	v_fmac_f32_dpp v241, v85, v141 row_shl:1 row_mask:0xf bank_mask:0xf
	v_fmac_f32_dpp v212, v94, v162 row_ror:1 row_mask:0xf bank_mask:0xf
	v_fmac_f32_dpp v213, v95, v163 row_ror:1 row_mask:0xf bank_mask:0xf
	v_fmac_f32_dpp v214, v96, v164 row_ror:1 row_mask:0xf bank_mask:0xf
	v_fmac_f32_dpp v215, v97, v165 row_ror:1 row_mask:0xf bank_mask:0xf
	v_fmac_f32_dpp v238, v90, v166 row_ror:1 row_mask:0xf bank_mask:0xf
	v_fmac_f32_dpp v239, v91, v167 row_ror:1 row_mask:0xf bank_mask:0xf
	v_fmac_f32_dpp v240, v92, v168 row_ror:1 row_mask:0xf bank_mask:0xf
	v_fmac_f32_dpp v241, v93, v169 row_ror:1 row_mask:0xf bank_mask:0xf
	v_fmac_f32_dpp v212, v78, v170 row_ror:15 row_mask:0xf bank_mask:0xf
	v_fmac_f32_dpp v213, v79, v171 row_ror:15 row_mask:0xf bank_mask:0xf
	v_fmac_f32_dpp v214, v80, v172 row_ror:15 row_mask:0xf bank_mask:0xf
	v_fmac_f32_dpp v215, v81, v173 row_ror:15 row_mask:0xf bank_mask:0xf
	v_fmac_f32_dpp v238, v74, v174 row_ror:15 row_mask:0xf bank_mask:0xf
	v_fmac_f32_dpp v239, v75, v175 row_ror:15 row_mask:0xf bank_mask:0xf
	v_fmac_f32_dpp v240, v76, v176 row_ror:15 row_mask:0xf bank_mask:0xf
	v_fmac_f32_dpp v241, v77, v177 row_ror:15 row_mask:0xf bank_mask:0xf
	v_pk_mul_f32 v[242:243], v[238:239], s[6:7] op_sel_hi:[1,0]
	v_pk_mul_f32 v[244:245], v[240:241], s[6:7] op_sel_hi:[1,0]
	v_exp_f32_e32 v242, v242
	v_exp_f32_e32 v243, v243
	v_exp_f32_e32 v244, v244
	v_exp_f32_e32 v245, v245
	v_add_f32_e32 v242, 1.0, v242
	v_add_f32_e32 v243, 1.0, v243
	v_add_f32_e32 v244, 1.0, v244
	v_add_f32_e32 v245, 1.0, v245
	v_rcp_f32_e32 v242, v242
	v_rcp_f32_e32 v243, v243
	v_rcp_f32_e32 v244, v244
	v_rcp_f32_e32 v245, v245
	s_nop 0
	v_pk_mul_f32 v[242:243], v[238:239], v[242:243]
	v_pk_mul_f32 v[244:245], v[240:241], v[244:245]
	v_pk_mul_f32 v[242:243], v[212:213], v[242:243]
	v_pk_mul_f32 v[244:245], v[214:215], v[244:245]
	v_cvt_pk_bf16_f32 v246, v242, v243
	v_cvt_pk_bf16_f32 v247, v244, v245
	s_add_u32 s26, s94, 0x18c000
	s_addc_u32 s27, s95, 0
	global_store_dwordx2 v217, v[246:247], s[26:27] offset:0
	v_pk_fma_f32 v[212:213], v[126:127], v[78:79], v[142:143]
	v_pk_fma_f32 v[214:215], v[128:129], v[80:81], v[144:145]
	v_pk_fma_f32 v[238:239], v[130:131], v[74:75], v[150:151]
	v_pk_fma_f32 v[240:241], v[132:133], v[76:77], v[152:153]
	v_fmac_f32_dpp v212, v78, v118 row_shr:1 row_mask:0xf bank_mask:0xf
	v_fmac_f32_dpp v213, v79, v119 row_shr:1 row_mask:0xf bank_mask:0xf
	v_fmac_f32_dpp v214, v80, v120 row_shr:1 row_mask:0xf bank_mask:0xf
	v_fmac_f32_dpp v215, v81, v121 row_shr:1 row_mask:0xf bank_mask:0xf
	v_fmac_f32_dpp v238, v74, v122 row_shr:1 row_mask:0xf bank_mask:0xf
	v_fmac_f32_dpp v239, v75, v123 row_shr:1 row_mask:0xf bank_mask:0xf
	v_fmac_f32_dpp v240, v76, v124 row_shr:1 row_mask:0xf bank_mask:0xf
	v_fmac_f32_dpp v241, v77, v125 row_shr:1 row_mask:0xf bank_mask:0xf
	v_fmac_f32_dpp v212, v78, v134 row_shl:1 row_mask:0xf bank_mask:0xf
	v_fmac_f32_dpp v213, v79, v135 row_shl:1 row_mask:0xf bank_mask:0xf
	v_fmac_f32_dpp v214, v80, v136 row_shl:1 row_mask:0xf bank_mask:0xf
	v_fmac_f32_dpp v215, v81, v137 row_shl:1 row_mask:0xf bank_mask:0xf
	v_fmac_f32_dpp v238, v74, v138 row_shl:1 row_mask:0xf bank_mask:0xf
	v_fmac_f32_dpp v239, v75, v139 row_shl:1 row_mask:0xf bank_mask:0xf
	v_fmac_f32_dpp v240, v76, v140 row_shl:1 row_mask:0xf bank_mask:0xf
	v_fmac_f32_dpp v241, v77, v141 row_shl:1 row_mask:0xf bank_mask:0xf
	v_fmac_f32_dpp v212, v86, v162 row_ror:1 row_mask:0xf bank_mask:0xf
	v_fmac_f32_dpp v213, v87, v163 row_ror:1 row_mask:0xf bank_mask:0xf
	v_fmac_f32_dpp v214, v88, v164 row_ror:1 row_mask:0xf bank_mask:0xf
	v_fmac_f32_dpp v215, v89, v165 row_ror:1 row_mask:0xf bank_mask:0xf
	v_fmac_f32_dpp v238, v82, v166 row_ror:1 row_mask:0xf bank_mask:0xf
	v_fmac_f32_dpp v239, v83, v167 row_ror:1 row_mask:0xf bank_mask:0xf
	v_fmac_f32_dpp v240, v84, v168 row_ror:1 row_mask:0xf bank_mask:0xf
	v_fmac_f32_dpp v241, v85, v169 row_ror:1 row_mask:0xf bank_mask:0xf
	v_fmac_f32_dpp v212, v66, v170 row_ror:15 row_mask:0xf bank_mask:0xf
	v_fmac_f32_dpp v213, v67, v171 row_ror:15 row_mask:0xf bank_mask:0xf
	v_fmac_f32_dpp v214, v68, v172 row_ror:15 row_mask:0xf bank_mask:0xf
	v_fmac_f32_dpp v215, v69, v173 row_ror:15 row_mask:0xf bank_mask:0xf
	v_fmac_f32_dpp v238, v70, v174 row_ror:15 row_mask:0xf bank_mask:0xf
	v_fmac_f32_dpp v239, v71, v175 row_ror:15 row_mask:0xf bank_mask:0xf
	v_fmac_f32_dpp v240, v72, v176 row_ror:15 row_mask:0xf bank_mask:0xf
	v_fmac_f32_dpp v241, v73, v177 row_ror:15 row_mask:0xf bank_mask:0xf
	v_pk_mul_f32 v[242:243], v[238:239], s[6:7] op_sel_hi:[1,0]
	v_pk_mul_f32 v[244:245], v[240:241], s[6:7] op_sel_hi:[1,0]
	v_exp_f32_e32 v242, v242
	v_exp_f32_e32 v243, v243
	v_exp_f32_e32 v244, v244
	v_exp_f32_e32 v245, v245
	v_add_f32_e32 v242, 1.0, v242
	v_add_f32_e32 v243, 1.0, v243
	v_add_f32_e32 v244, 1.0, v244
	v_add_f32_e32 v245, 1.0, v245
	v_rcp_f32_e32 v242, v242
	v_rcp_f32_e32 v243, v243
	v_rcp_f32_e32 v244, v244
	v_rcp_f32_e32 v245, v245
	s_nop 0
	v_pk_mul_f32 v[242:243], v[238:239], v[242:243]
	v_pk_mul_f32 v[244:245], v[240:241], v[244:245]
	v_pk_mul_f32 v[242:243], v[212:213], v[242:243]
	v_pk_mul_f32 v[244:245], v[214:215], v[244:245]
	v_cvt_pk_bf16_f32 v246, v242, v243
	v_cvt_pk_bf16_f32 v247, v244, v245
	s_add_u32 s26, s94, 0x1b8000
	s_addc_u32 s27, s95, 0
	global_store_dwordx2 v217, v[246:247], s[26:27] offset:0
	v_pk_fma_f32 v[212:213], v[126:127], v[66:67], v[142:143]
	v_pk_fma_f32 v[214:215], v[128:129], v[68:69], v[144:145]
	v_pk_fma_f32 v[238:239], v[130:131], v[70:71], v[150:151]
	v_pk_fma_f32 v[240:241], v[132:133], v[72:73], v[152:153]
	v_fmac_f32_dpp v212, v66, v118 row_shr:1 row_mask:0xf bank_mask:0xf
	v_fmac_f32_dpp v213, v67, v119 row_shr:1 row_mask:0xf bank_mask:0xf
	v_fmac_f32_dpp v214, v68, v120 row_shr:1 row_mask:0xf bank_mask:0xf
	v_fmac_f32_dpp v215, v69, v121 row_shr:1 row_mask:0xf bank_mask:0xf
	v_fmac_f32_dpp v238, v70, v122 row_shr:1 row_mask:0xf bank_mask:0xf
	v_fmac_f32_dpp v239, v71, v123 row_shr:1 row_mask:0xf bank_mask:0xf
	v_fmac_f32_dpp v240, v72, v124 row_shr:1 row_mask:0xf bank_mask:0xf
	v_fmac_f32_dpp v241, v73, v125 row_shr:1 row_mask:0xf bank_mask:0xf
	v_fmac_f32_dpp v212, v66, v134 row_shl:1 row_mask:0xf bank_mask:0xf
	v_fmac_f32_dpp v213, v67, v135 row_shl:1 row_mask:0xf bank_mask:0xf
	v_fmac_f32_dpp v214, v68, v136 row_shl:1 row_mask:0xf bank_mask:0xf
	v_fmac_f32_dpp v215, v69, v137 row_shl:1 row_mask:0xf bank_mask:0xf
	v_fmac_f32_dpp v238, v70, v138 row_shl:1 row_mask:0xf bank_mask:0xf
	v_fmac_f32_dpp v239, v71, v139 row_shl:1 row_mask:0xf bank_mask:0xf
	v_fmac_f32_dpp v240, v72, v140 row_shl:1 row_mask:0xf bank_mask:0xf
	v_fmac_f32_dpp v241, v73, v141 row_shl:1 row_mask:0xf bank_mask:0xf
	v_fmac_f32_dpp v212, v78, v162 row_ror:1 row_mask:0xf bank_mask:0xf
	v_fmac_f32_dpp v213, v79, v163 row_ror:1 row_mask:0xf bank_mask:0xf
	v_fmac_f32_dpp v214, v80, v164 row_ror:1 row_mask:0xf bank_mask:0xf
	v_fmac_f32_dpp v215, v81, v165 row_ror:1 row_mask:0xf bank_mask:0xf
	v_fmac_f32_dpp v238, v74, v166 row_ror:1 row_mask:0xf bank_mask:0xf
	v_fmac_f32_dpp v239, v75, v167 row_ror:1 row_mask:0xf bank_mask:0xf
	v_fmac_f32_dpp v240, v76, v168 row_ror:1 row_mask:0xf bank_mask:0xf
	v_fmac_f32_dpp v241, v77, v169 row_ror:1 row_mask:0xf bank_mask:0xf
	s_cmp_eq_u32 s4, 64
	s_cbranch_scc1 .Lupc_3
	v_pk_fma_f32 v[212:213], v[188:189], v[170:171], v[212:213]
	v_pk_fma_f32 v[214:215], v[190:191], v[172:173], v[214:215]
	v_pk_fma_f32 v[238:239], v[192:193], v[174:175], v[238:239]
	v_pk_fma_f32 v[240:241], v[194:195], v[176:177], v[240:241]
.Lupc_3:
	s_cmp_lg_u32 s4, 64
	s_cbranch_scc1 .Lupc_4
	s_mov_b64 exec, s[40:41]
	s_lshl_b32 s7, s72, 1
	s_or_b32 s7, s7, 1
	s_mul_i32 s7, s7, 0xb000
	v_readlane_b32 s26, v255, 0
	v_readlane_b32 s27, v255, 1
	s_add_u32 s26, s26, s7
	s_addc_u32 s27, s27, 0
	global_store_dwordx4 v196, v[66:69], s[26:27] offset:0
	s_add_u32 s26, s26, 22528
	s_addc_u32 s27, s27, 0
	global_store_dwordx4 v196, v[70:73], s[26:27] offset:0
	v_readlane_b32 s26, v255, 15
	v_readlane_b32 s27, v255, 16
	s_add_u32 s26, s26, s7
	s_addc_u32 s27, s27, 0
	global_store_dwordx4 v196, v[212:215], s[26:27] offset:0
	s_add_u32 s26, s26, 22528
	s_addc_u32 s27, s27, 0
	global_store_dwordx4 v196, v[238:241], s[26:27] offset:0
	s_mov_b64 exec, -1
.Lupc_4:
	v_pk_mul_f32 v[242:243], v[238:239], s[6:7] op_sel_hi:[1,0]
	v_pk_mul_f32 v[244:245], v[240:241], s[6:7] op_sel_hi:[1,0]
	v_exp_f32_e32 v242, v242
	v_exp_f32_e32 v243, v243
	v_exp_f32_e32 v244, v244
	v_exp_f32_e32 v245, v245
	v_add_f32_e32 v242, 1.0, v242
	v_add_f32_e32 v243, 1.0, v243
	v_add_f32_e32 v244, 1.0, v244
	v_add_f32_e32 v245, 1.0, v245
	v_rcp_f32_e32 v242, v242
	v_rcp_f32_e32 v243, v243
	v_rcp_f32_e32 v244, v244
	v_rcp_f32_e32 v245, v245
	s_nop 0
	v_pk_mul_f32 v[242:243], v[238:239], v[242:243]
	v_pk_mul_f32 v[244:245], v[240:241], v[244:245]
	v_pk_mul_f32 v[242:243], v[212:213], v[242:243]
	v_pk_mul_f32 v[244:245], v[214:215], v[244:245]
	v_cvt_pk_bf16_f32 v246, v242, v243
	v_cvt_pk_bf16_f32 v247, v244, v245
	s_add_u32 s26, s94, 0x1e4000
	s_addc_u32 s27, s95, 0
	global_store_dwordx2 v217, v[246:247], s[26:27] offset:0
	ds_read_b128 v[188:191], v216 offset:16
	ds_read_b128 v[192:195], v216 offset:528
	s_waitcnt vmcnt(4)
	v_cndmask_b32_e64 v162, 0, v158, s[38:39]
	v_cndmask_b32_e64 v170, 0, v110, s[40:41]
	v_cndmask_b32_e64 v163, 0, v159, s[38:39]
	v_cndmask_b32_e64 v171, 0, v111, s[40:41]
	v_cndmask_b32_e64 v164, 0, v160, s[38:39]
	v_cndmask_b32_e64 v172, 0, v112, s[40:41]
	v_cndmask_b32_e64 v165, 0, v161, s[38:39]
	v_cndmask_b32_e64 v173, 0, v113, s[40:41]
	v_cndmask_b32_e64 v166, 0, v154, s[38:39]
	v_cndmask_b32_e64 v174, 0, v106, s[40:41]
	v_cndmask_b32_e64 v167, 0, v155, s[38:39]
	v_cndmask_b32_e64 v175, 0, v107, s[40:41]
	v_cndmask_b32_e64 v168, 0, v156, s[38:39]
	v_cndmask_b32_e64 v176, 0, v108, s[40:41]
	v_cndmask_b32_e64 v169, 0, v157, s[38:39]
	v_cndmask_b32_e64 v177, 0, v109, s[40:41]
	v_pk_fma_f32 v[212:213], v[146:147], v[62:63], v[102:103]
	v_pk_fma_f32 v[214:215], v[148:149], v[64:65], v[104:105]
	v_pk_fma_f32 v[238:239], v[114:115], v[58:59], v[98:99]
	v_pk_fma_f32 v[240:241], v[116:117], v[60:61], v[100:101]
	v_fmac_f32_dpp v212, v62, v158 row_shr:1 row_mask:0xf bank_mask:0xf
	v_fmac_f32_dpp v213, v63, v159 row_shr:1 row_mask:0xf bank_mask:0xf
	v_fmac_f32_dpp v214, v64, v160 row_shr:1 row_mask:0xf bank_mask:0xf
	v_fmac_f32_dpp v215, v65, v161 row_shr:1 row_mask:0xf bank_mask:0xf
	v_fmac_f32_dpp v238, v58, v154 row_shr:1 row_mask:0xf bank_mask:0xf
	v_fmac_f32_dpp v239, v59, v155 row_shr:1 row_mask:0xf bank_mask:0xf
	v_fmac_f32_dpp v240, v60, v156 row_shr:1 row_mask:0xf bank_mask:0xf
	v_fmac_f32_dpp v241, v61, v157 row_shr:1 row_mask:0xf bank_mask:0xf
	v_fmac_f32_dpp v212, v62, v110 row_shl:1 row_mask:0xf bank_mask:0xf
	v_fmac_f32_dpp v213, v63, v111 row_shl:1 row_mask:0xf bank_mask:0xf
	v_fmac_f32_dpp v214, v64, v112 row_shl:1 row_mask:0xf bank_mask:0xf
	v_fmac_f32_dpp v215, v65, v113 row_shl:1 row_mask:0xf bank_mask:0xf
	v_fmac_f32_dpp v238, v58, v106 row_shl:1 row_mask:0xf bank_mask:0xf
	v_fmac_f32_dpp v239, v59, v107 row_shl:1 row_mask:0xf bank_mask:0xf
	v_fmac_f32_dpp v240, v60, v108 row_shl:1 row_mask:0xf bank_mask:0xf
	v_fmac_f32_dpp v241, v61, v109 row_shl:1 row_mask:0xf bank_mask:0xf
	s_waitcnt lgkmcnt(0)
	s_cmp_eq_u32 s4, 0
	s_cbranch_scc1 .Lupc_5
	v_pk_fma_f32 v[212:213], v[188:189], v[162:163], v[212:213]
	v_pk_fma_f32 v[214:215], v[190:191], v[164:165], v[214:215]
	v_pk_fma_f32 v[238:239], v[192:193], v[166:167], v[238:239]
	v_pk_fma_f32 v[240:241], v[194:195], v[168:169], v[240:241]
.Lupc_5:
	v_fmac_f32_dpp v212, v54, v170 row_ror:15 row_mask:0xf bank_mask:0xf
	v_fmac_f32_dpp v213, v55, v171 row_ror:15 row_mask:0xf bank_mask:0xf
	v_fmac_f32_dpp v214, v56, v172 row_ror:15 row_mask:0xf bank_mask:0xf
	v_fmac_f32_dpp v215, v57, v173 row_ror:15 row_mask:0xf bank_mask:0xf
	v_fmac_f32_dpp v238, v50, v174 row_ror:15 row_mask:0xf bank_mask:0xf
	v_fmac_f32_dpp v239, v51, v175 row_ror:15 row_mask:0xf bank_mask:0xf
	v_fmac_f32_dpp v240, v52, v176 row_ror:15 row_mask:0xf bank_mask:0xf
	v_fmac_f32_dpp v241, v53, v177 row_ror:15 row_mask:0xf bank_mask:0xf
	s_cmp_lg_u32 s4, 0
	s_cbranch_scc1 .Lupc_6
	s_mov_b64 exec, s[38:39]
	s_lshl_b32 s7, s72, 1
	s_mul_i32 s7, s7, 0xb000
	v_readlane_b32 s26, v255, 0
	v_readlane_b32 s27, v255, 1
	s_add_u32 s26, s26, s7
	s_addc_u32 s27, s27, 0
	global_store_dwordx4 v196, v[62:65], s[26:27] offset:16
	s_add_u32 s26, s26, 22528
	s_addc_u32 s27, s27, 0
	global_store_dwordx4 v196, v[58:61], s[26:27] offset:16
	v_readlane_b32 s26, v255, 15
	v_readlane_b32 s27, v255, 16
	s_add_u32 s26, s26, s7
	s_addc_u32 s27, s27, 0
	global_store_dwordx4 v196, v[212:215], s[26:27] offset:16
	s_add_u32 s26, s26, 22528
	s_addc_u32 s27, s27, 0
	global_store_dwordx4 v196, v[238:241], s[26:27] offset:16
	s_mov_b64 exec, -1
.Lupc_6:
	v_pk_mul_f32 v[242:243], v[238:239], s[6:7] op_sel_hi:[1,0]
	v_pk_mul_f32 v[244:245], v[240:241], s[6:7] op_sel_hi:[1,0]
	v_exp_f32_e32 v242, v242
	v_exp_f32_e32 v243, v243
	v_exp_f32_e32 v244, v244
	v_exp_f32_e32 v245, v245
	v_add_f32_e32 v242, 1.0, v242
	v_add_f32_e32 v243, 1.0, v243
	v_add_f32_e32 v244, 1.0, v244
	v_add_f32_e32 v245, 1.0, v245
	v_rcp_f32_e32 v242, v242
	v_rcp_f32_e32 v243, v243
	v_rcp_f32_e32 v244, v244
	v_rcp_f32_e32 v245, v245
	s_nop 0
	v_pk_mul_f32 v[242:243], v[238:239], v[242:243]
	v_pk_mul_f32 v[244:245], v[240:241], v[244:245]
	v_pk_mul_f32 v[242:243], v[212:213], v[242:243]
	v_pk_mul_f32 v[244:245], v[214:215], v[244:245]
	v_cvt_pk_bf16_f32 v246, v242, v243
	v_cvt_pk_bf16_f32 v247, v244, v245
	global_store_dwordx2 v217, v[246:247], s[94:95] offset:8
	v_pk_fma_f32 v[212:213], v[146:147], v[54:55], v[102:103]
	v_pk_fma_f32 v[214:215], v[148:149], v[56:57], v[104:105]
	v_pk_fma_f32 v[238:239], v[114:115], v[50:51], v[98:99]
	v_pk_fma_f32 v[240:241], v[116:117], v[52:53], v[100:101]
	v_fmac_f32_dpp v212, v54, v158 row_shr:1 row_mask:0xf bank_mask:0xf
	v_fmac_f32_dpp v213, v55, v159 row_shr:1 row_mask:0xf bank_mask:0xf
	v_fmac_f32_dpp v214, v56, v160 row_shr:1 row_mask:0xf bank_mask:0xf
	v_fmac_f32_dpp v215, v57, v161 row_shr:1 row_mask:0xf bank_mask:0xf
	v_fmac_f32_dpp v238, v50, v154 row_shr:1 row_mask:0xf bank_mask:0xf
	v_fmac_f32_dpp v239, v51, v155 row_shr:1 row_mask:0xf bank_mask:0xf
	v_fmac_f32_dpp v240, v52, v156 row_shr:1 row_mask:0xf bank_mask:0xf
	v_fmac_f32_dpp v241, v53, v157 row_shr:1 row_mask:0xf bank_mask:0xf
	v_fmac_f32_dpp v212, v54, v110 row_shl:1 row_mask:0xf bank_mask:0xf
	v_fmac_f32_dpp v213, v55, v111 row_shl:1 row_mask:0xf bank_mask:0xf
	v_fmac_f32_dpp v214, v56, v112 row_shl:1 row_mask:0xf bank_mask:0xf
	v_fmac_f32_dpp v215, v57, v113 row_shl:1 row_mask:0xf bank_mask:0xf
	v_fmac_f32_dpp v238, v50, v106 row_shl:1 row_mask:0xf bank_mask:0xf
	v_fmac_f32_dpp v239, v51, v107 row_shl:1 row_mask:0xf bank_mask:0xf
	v_fmac_f32_dpp v240, v52, v108 row_shl:1 row_mask:0xf bank_mask:0xf
	v_fmac_f32_dpp v241, v53, v109 row_shl:1 row_mask:0xf bank_mask:0xf
	v_fmac_f32_dpp v212, v62, v162 row_ror:1 row_mask:0xf bank_mask:0xf
	v_fmac_f32_dpp v213, v63, v163 row_ror:1 row_mask:0xf bank_mask:0xf
	v_fmac_f32_dpp v214, v64, v164 row_ror:1 row_mask:0xf bank_mask:0xf
	v_fmac_f32_dpp v215, v65, v165 row_ror:1 row_mask:0xf bank_mask:0xf
	v_fmac_f32_dpp v238, v58, v166 row_ror:1 row_mask:0xf bank_mask:0xf
	v_fmac_f32_dpp v239, v59, v167 row_ror:1 row_mask:0xf bank_mask:0xf
	v_fmac_f32_dpp v240, v60, v168 row_ror:1 row_mask:0xf bank_mask:0xf
	v_fmac_f32_dpp v241, v61, v169 row_ror:1 row_mask:0xf bank_mask:0xf
	v_fmac_f32_dpp v212, v46, v170 row_ror:15 row_mask:0xf bank_mask:0xf
	v_fmac_f32_dpp v213, v47, v171 row_ror:15 row_mask:0xf bank_mask:0xf
	v_fmac_f32_dpp v214, v48, v172 row_ror:15 row_mask:0xf bank_mask:0xf
	v_fmac_f32_dpp v215, v49, v173 row_ror:15 row_mask:0xf bank_mask:0xf
	v_fmac_f32_dpp v238, v42, v174 row_ror:15 row_mask:0xf bank_mask:0xf
	v_fmac_f32_dpp v239, v43, v175 row_ror:15 row_mask:0xf bank_mask:0xf
	v_fmac_f32_dpp v240, v44, v176 row_ror:15 row_mask:0xf bank_mask:0xf
	v_fmac_f32_dpp v241, v45, v177 row_ror:15 row_mask:0xf bank_mask:0xf
	v_pk_mul_f32 v[242:243], v[238:239], s[6:7] op_sel_hi:[1,0]
	v_pk_mul_f32 v[244:245], v[240:241], s[6:7] op_sel_hi:[1,0]
	v_exp_f32_e32 v242, v242
	v_exp_f32_e32 v243, v243
	v_exp_f32_e32 v244, v244
	v_exp_f32_e32 v245, v245
	v_add_f32_e32 v242, 1.0, v242
	v_add_f32_e32 v243, 1.0, v243
	v_add_f32_e32 v244, 1.0, v244
	v_add_f32_e32 v245, 1.0, v245
	v_rcp_f32_e32 v242, v242
	v_rcp_f32_e32 v243, v243
	v_rcp_f32_e32 v244, v244
	v_rcp_f32_e32 v245, v245
	s_nop 0
	v_pk_mul_f32 v[242:243], v[238:239], v[242:243]
	v_pk_mul_f32 v[244:245], v[240:241], v[244:245]
	v_pk_mul_f32 v[242:243], v[212:213], v[242:243]
	v_pk_mul_f32 v[244:245], v[214:215], v[244:245]
	v_cvt_pk_bf16_f32 v246, v242, v243
	v_cvt_pk_bf16_f32 v247, v244, v245
	s_add_u32 s26, s94, 0x2c000
	s_addc_u32 s27, s95, 0
	global_store_dwordx2 v217, v[246:247], s[26:27] offset:8
	v_pk_fma_f32 v[212:213], v[146:147], v[46:47], v[102:103]
	v_pk_fma_f32 v[214:215], v[148:149], v[48:49], v[104:105]
	v_pk_fma_f32 v[238:239], v[114:115], v[42:43], v[98:99]
	v_pk_fma_f32 v[240:241], v[116:117], v[44:45], v[100:101]
	v_fmac_f32_dpp v212, v46, v158 row_shr:1 row_mask:0xf bank_mask:0xf
	v_fmac_f32_dpp v213, v47, v159 row_shr:1 row_mask:0xf bank_mask:0xf
	v_fmac_f32_dpp v214, v48, v160 row_shr:1 row_mask:0xf bank_mask:0xf
	v_fmac_f32_dpp v215, v49, v161 row_shr:1 row_mask:0xf bank_mask:0xf
	v_fmac_f32_dpp v238, v42, v154 row_shr:1 row_mask:0xf bank_mask:0xf
	v_fmac_f32_dpp v239, v43, v155 row_shr:1 row_mask:0xf bank_mask:0xf
	v_fmac_f32_dpp v240, v44, v156 row_shr:1 row_mask:0xf bank_mask:0xf
	v_fmac_f32_dpp v241, v45, v157 row_shr:1 row_mask:0xf bank_mask:0xf
	v_fmac_f32_dpp v212, v46, v110 row_shl:1 row_mask:0xf bank_mask:0xf
	v_fmac_f32_dpp v213, v47, v111 row_shl:1 row_mask:0xf bank_mask:0xf
	v_fmac_f32_dpp v214, v48, v112 row_shl:1 row_mask:0xf bank_mask:0xf
	v_fmac_f32_dpp v215, v49, v113 row_shl:1 row_mask:0xf bank_mask:0xf
	v_fmac_f32_dpp v238, v42, v106 row_shl:1 row_mask:0xf bank_mask:0xf
	v_fmac_f32_dpp v239, v43, v107 row_shl:1 row_mask:0xf bank_mask:0xf
	v_fmac_f32_dpp v240, v44, v108 row_shl:1 row_mask:0xf bank_mask:0xf
	v_fmac_f32_dpp v241, v45, v109 row_shl:1 row_mask:0xf bank_mask:0xf
	v_fmac_f32_dpp v212, v54, v162 row_ror:1 row_mask:0xf bank_mask:0xf
	v_fmac_f32_dpp v213, v55, v163 row_ror:1 row_mask:0xf bank_mask:0xf
	v_fmac_f32_dpp v214, v56, v164 row_ror:1 row_mask:0xf bank_mask:0xf
	v_fmac_f32_dpp v215, v57, v165 row_ror:1 row_mask:0xf bank_mask:0xf
	v_fmac_f32_dpp v238, v50, v166 row_ror:1 row_mask:0xf bank_mask:0xf
	v_fmac_f32_dpp v239, v51, v167 row_ror:1 row_mask:0xf bank_mask:0xf
	v_fmac_f32_dpp v240, v52, v168 row_ror:1 row_mask:0xf bank_mask:0xf
	v_fmac_f32_dpp v241, v53, v169 row_ror:1 row_mask:0xf bank_mask:0xf
	v_fmac_f32_dpp v212, v38, v170 row_ror:15 row_mask:0xf bank_mask:0xf
	v_fmac_f32_dpp v213, v39, v171 row_ror:15 row_mask:0xf bank_mask:0xf
	v_fmac_f32_dpp v214, v40, v172 row_ror:15 row_mask:0xf bank_mask:0xf
	v_fmac_f32_dpp v215, v41, v173 row_ror:15 row_mask:0xf bank_mask:0xf
	v_fmac_f32_dpp v238, v34, v174 row_ror:15 row_mask:0xf bank_mask:0xf
	v_fmac_f32_dpp v239, v35, v175 row_ror:15 row_mask:0xf bank_mask:0xf
	v_fmac_f32_dpp v240, v36, v176 row_ror:15 row_mask:0xf bank_mask:0xf
	v_fmac_f32_dpp v241, v37, v177 row_ror:15 row_mask:0xf bank_mask:0xf
	v_pk_mul_f32 v[242:243], v[238:239], s[6:7] op_sel_hi:[1,0]
	v_pk_mul_f32 v[244:245], v[240:241], s[6:7] op_sel_hi:[1,0]
	v_exp_f32_e32 v242, v242
	v_exp_f32_e32 v243, v243
	v_exp_f32_e32 v244, v244
	v_exp_f32_e32 v245, v245
	v_add_f32_e32 v242, 1.0, v242
	v_add_f32_e32 v243, 1.0, v243
	v_add_f32_e32 v244, 1.0, v244
	v_add_f32_e32 v245, 1.0, v245
	v_rcp_f32_e32 v242, v242
	v_rcp_f32_e32 v243, v243
	v_rcp_f32_e32 v244, v244
	v_rcp_f32_e32 v245, v245
	s_nop 0
	v_pk_mul_f32 v[242:243], v[238:239], v[242:243]
	v_pk_mul_f32 v[244:245], v[240:241], v[244:245]
	v_pk_mul_f32 v[242:243], v[212:213], v[242:243]
	v_pk_mul_f32 v[244:245], v[214:215], v[244:245]
	v_cvt_pk_bf16_f32 v246, v242, v243
	v_cvt_pk_bf16_f32 v247, v244, v245
	s_add_u32 s26, s94, 0x58000
	s_addc_u32 s27, s95, 0
	global_store_dwordx2 v217, v[246:247], s[26:27] offset:8
	v_pk_fma_f32 v[212:213], v[146:147], v[38:39], v[102:103]
	v_pk_fma_f32 v[214:215], v[148:149], v[40:41], v[104:105]
	v_pk_fma_f32 v[238:239], v[114:115], v[34:35], v[98:99]
	v_pk_fma_f32 v[240:241], v[116:117], v[36:37], v[100:101]
	v_fmac_f32_dpp v212, v38, v158 row_shr:1 row_mask:0xf bank_mask:0xf
	v_fmac_f32_dpp v213, v39, v159 row_shr:1 row_mask:0xf bank_mask:0xf
	v_fmac_f32_dpp v214, v40, v160 row_shr:1 row_mask:0xf bank_mask:0xf
	v_fmac_f32_dpp v215, v41, v161 row_shr:1 row_mask:0xf bank_mask:0xf
	v_fmac_f32_dpp v238, v34, v154 row_shr:1 row_mask:0xf bank_mask:0xf
	v_fmac_f32_dpp v239, v35, v155 row_shr:1 row_mask:0xf bank_mask:0xf
	v_fmac_f32_dpp v240, v36, v156 row_shr:1 row_mask:0xf bank_mask:0xf
	v_fmac_f32_dpp v241, v37, v157 row_shr:1 row_mask:0xf bank_mask:0xf
	v_fmac_f32_dpp v212, v38, v110 row_shl:1 row_mask:0xf bank_mask:0xf
	v_fmac_f32_dpp v213, v39, v111 row_shl:1 row_mask:0xf bank_mask:0xf
	v_fmac_f32_dpp v214, v40, v112 row_shl:1 row_mask:0xf bank_mask:0xf
	v_fmac_f32_dpp v215, v41, v113 row_shl:1 row_mask:0xf bank_mask:0xf
	v_fmac_f32_dpp v238, v34, v106 row_shl:1 row_mask:0xf bank_mask:0xf
	v_fmac_f32_dpp v239, v35, v107 row_shl:1 row_mask:0xf bank_mask:0xf
	v_fmac_f32_dpp v240, v36, v108 row_shl:1 row_mask:0xf bank_mask:0xf
	v_fmac_f32_dpp v241, v37, v109 row_shl:1 row_mask:0xf bank_mask:0xf
	v_fmac_f32_dpp v212, v46, v162 row_ror:1 row_mask:0xf bank_mask:0xf
	v_fmac_f32_dpp v213, v47, v163 row_ror:1 row_mask:0xf bank_mask:0xf
	v_fmac_f32_dpp v214, v48, v164 row_ror:1 row_mask:0xf bank_mask:0xf
	v_fmac_f32_dpp v215, v49, v165 row_ror:1 row_mask:0xf bank_mask:0xf
	v_fmac_f32_dpp v238, v42, v166 row_ror:1 row_mask:0xf bank_mask:0xf
	v_fmac_f32_dpp v239, v43, v167 row_ror:1 row_mask:0xf bank_mask:0xf
	v_fmac_f32_dpp v240, v44, v168 row_ror:1 row_mask:0xf bank_mask:0xf
	v_fmac_f32_dpp v241, v45, v169 row_ror:1 row_mask:0xf bank_mask:0xf
	v_pk_fma_f32 v[212:213], v[188:189], v[170:171], v[212:213]
	v_pk_fma_f32 v[214:215], v[190:191], v[172:173], v[214:215]
	v_pk_fma_f32 v[238:239], v[192:193], v[174:175], v[238:239]
	v_pk_fma_f32 v[240:241], v[194:195], v[176:177], v[240:241]
	v_pk_mul_f32 v[242:243], v[238:239], s[6:7] op_sel_hi:[1,0]
	v_pk_mul_f32 v[244:245], v[240:241], s[6:7] op_sel_hi:[1,0]
	v_exp_f32_e32 v242, v242
	v_exp_f32_e32 v243, v243
	v_exp_f32_e32 v244, v244
	v_exp_f32_e32 v245, v245
	v_add_f32_e32 v242, 1.0, v242
	v_add_f32_e32 v243, 1.0, v243
	v_add_f32_e32 v244, 1.0, v244
	v_add_f32_e32 v245, 1.0, v245
	v_rcp_f32_e32 v242, v242
	v_rcp_f32_e32 v243, v243
	v_rcp_f32_e32 v244, v244
	v_rcp_f32_e32 v245, v245
	s_nop 0
	v_pk_mul_f32 v[242:243], v[238:239], v[242:243]
	v_pk_mul_f32 v[244:245], v[240:241], v[244:245]
	v_pk_mul_f32 v[242:243], v[212:213], v[242:243]
	v_pk_mul_f32 v[244:245], v[214:215], v[244:245]
	v_cvt_pk_bf16_f32 v246, v242, v243
	v_cvt_pk_bf16_f32 v247, v244, v245
	s_add_u32 s26, s94, 0x84000
	s_addc_u32 s27, s95, 0
	global_store_dwordx2 v217, v[246:247], s[26:27] offset:8
	ds_read_b128 v[188:191], v197 offset:4112
	ds_read_b128 v[192:195], v197 offset:4624
	v_pk_fma_f32 v[212:213], v[146:147], v[30:31], v[102:103]
	v_pk_fma_f32 v[214:215], v[148:149], v[32:33], v[104:105]
	v_pk_fma_f32 v[238:239], v[114:115], v[26:27], v[98:99]
	v_pk_fma_f32 v[240:241], v[116:117], v[28:29], v[100:101]
	v_fmac_f32_dpp v212, v30, v158 row_shr:1 row_mask:0xf bank_mask:0xf
	v_fmac_f32_dpp v213, v31, v159 row_shr:1 row_mask:0xf bank_mask:0xf
	v_fmac_f32_dpp v214, v32, v160 row_shr:1 row_mask:0xf bank_mask:0xf
	v_fmac_f32_dpp v215, v33, v161 row_shr:1 row_mask:0xf bank_mask:0xf
	v_fmac_f32_dpp v238, v26, v154 row_shr:1 row_mask:0xf bank_mask:0xf
	v_fmac_f32_dpp v239, v27, v155 row_shr:1 row_mask:0xf bank_mask:0xf
	v_fmac_f32_dpp v240, v28, v156 row_shr:1 row_mask:0xf bank_mask:0xf
	v_fmac_f32_dpp v241, v29, v157 row_shr:1 row_mask:0xf bank_mask:0xf
	v_fmac_f32_dpp v212, v30, v110 row_shl:1 row_mask:0xf bank_mask:0xf
	v_fmac_f32_dpp v213, v31, v111 row_shl:1 row_mask:0xf bank_mask:0xf
	v_fmac_f32_dpp v214, v32, v112 row_shl:1 row_mask:0xf bank_mask:0xf
	v_fmac_f32_dpp v215, v33, v113 row_shl:1 row_mask:0xf bank_mask:0xf
	v_fmac_f32_dpp v238, v26, v106 row_shl:1 row_mask:0xf bank_mask:0xf
	v_fmac_f32_dpp v239, v27, v107 row_shl:1 row_mask:0xf bank_mask:0xf
	v_fmac_f32_dpp v240, v28, v108 row_shl:1 row_mask:0xf bank_mask:0xf
	v_fmac_f32_dpp v241, v29, v109 row_shl:1 row_mask:0xf bank_mask:0xf
	s_waitcnt lgkmcnt(0)
	v_pk_fma_f32 v[212:213], v[188:189], v[162:163], v[212:213]
	v_pk_fma_f32 v[214:215], v[190:191], v[164:165], v[214:215]
	v_pk_fma_f32 v[238:239], v[192:193], v[166:167], v[238:239]
	v_pk_fma_f32 v[240:241], v[194:195], v[168:169], v[240:241]
	v_fmac_f32_dpp v212, v22, v170 row_ror:15 row_mask:0xf bank_mask:0xf
	v_fmac_f32_dpp v213, v23, v171 row_ror:15 row_mask:0xf bank_mask:0xf
	v_fmac_f32_dpp v214, v24, v172 row_ror:15 row_mask:0xf bank_mask:0xf
	v_fmac_f32_dpp v215, v25, v173 row_ror:15 row_mask:0xf bank_mask:0xf
	v_fmac_f32_dpp v238, v18, v174 row_ror:15 row_mask:0xf bank_mask:0xf
	v_fmac_f32_dpp v239, v19, v175 row_ror:15 row_mask:0xf bank_mask:0xf
	v_fmac_f32_dpp v240, v20, v176 row_ror:15 row_mask:0xf bank_mask:0xf
	v_fmac_f32_dpp v241, v21, v177 row_ror:15 row_mask:0xf bank_mask:0xf
	v_pk_mul_f32 v[242:243], v[238:239], s[6:7] op_sel_hi:[1,0]
	v_pk_mul_f32 v[244:245], v[240:241], s[6:7] op_sel_hi:[1,0]
	v_exp_f32_e32 v242, v242
	v_exp_f32_e32 v243, v243
	v_exp_f32_e32 v244, v244
	v_exp_f32_e32 v245, v245
	v_add_f32_e32 v242, 1.0, v242
	v_add_f32_e32 v243, 1.0, v243
	v_add_f32_e32 v244, 1.0, v244
	v_add_f32_e32 v245, 1.0, v245
	v_rcp_f32_e32 v242, v242
	v_rcp_f32_e32 v243, v243
	v_rcp_f32_e32 v244, v244
	v_rcp_f32_e32 v245, v245
	s_nop 0
	v_pk_mul_f32 v[242:243], v[238:239], v[242:243]
	v_pk_mul_f32 v[244:245], v[240:241], v[244:245]
	v_pk_mul_f32 v[242:243], v[212:213], v[242:243]
	v_pk_mul_f32 v[244:245], v[214:215], v[244:245]
	v_cvt_pk_bf16_f32 v246, v242, v243
	v_cvt_pk_bf16_f32 v247, v244, v245
	s_add_u32 s26, s94, 0x160000
	s_addc_u32 s27, s95, 0
	global_store_dwordx2 v217, v[246:247], s[26:27] offset:8
	v_pk_fma_f32 v[212:213], v[146:147], v[22:23], v[102:103]
	v_pk_fma_f32 v[214:215], v[148:149], v[24:25], v[104:105]
	v_pk_fma_f32 v[238:239], v[114:115], v[18:19], v[98:99]
	v_pk_fma_f32 v[240:241], v[116:117], v[20:21], v[100:101]
	v_fmac_f32_dpp v212, v22, v158 row_shr:1 row_mask:0xf bank_mask:0xf
	v_fmac_f32_dpp v213, v23, v159 row_shr:1 row_mask:0xf bank_mask:0xf
	v_fmac_f32_dpp v214, v24, v160 row_shr:1 row_mask:0xf bank_mask:0xf
	v_fmac_f32_dpp v215, v25, v161 row_shr:1 row_mask:0xf bank_mask:0xf
	v_fmac_f32_dpp v238, v18, v154 row_shr:1 row_mask:0xf bank_mask:0xf
	v_fmac_f32_dpp v239, v19, v155 row_shr:1 row_mask:0xf bank_mask:0xf
	v_fmac_f32_dpp v240, v20, v156 row_shr:1 row_mask:0xf bank_mask:0xf
	v_fmac_f32_dpp v241, v21, v157 row_shr:1 row_mask:0xf bank_mask:0xf
	v_fmac_f32_dpp v212, v22, v110 row_shl:1 row_mask:0xf bank_mask:0xf
	v_fmac_f32_dpp v213, v23, v111 row_shl:1 row_mask:0xf bank_mask:0xf
	v_fmac_f32_dpp v214, v24, v112 row_shl:1 row_mask:0xf bank_mask:0xf
	v_fmac_f32_dpp v215, v25, v113 row_shl:1 row_mask:0xf bank_mask:0xf
	v_fmac_f32_dpp v238, v18, v106 row_shl:1 row_mask:0xf bank_mask:0xf
	v_fmac_f32_dpp v239, v19, v107 row_shl:1 row_mask:0xf bank_mask:0xf
	v_fmac_f32_dpp v240, v20, v108 row_shl:1 row_mask:0xf bank_mask:0xf
	v_fmac_f32_dpp v241, v21, v109 row_shl:1 row_mask:0xf bank_mask:0xf
	v_fmac_f32_dpp v212, v30, v162 row_ror:1 row_mask:0xf bank_mask:0xf
	v_fmac_f32_dpp v213, v31, v163 row_ror:1 row_mask:0xf bank_mask:0xf
	v_fmac_f32_dpp v214, v32, v164 row_ror:1 row_mask:0xf bank_mask:0xf
	v_fmac_f32_dpp v215, v33, v165 row_ror:1 row_mask:0xf bank_mask:0xf
	v_fmac_f32_dpp v238, v26, v166 row_ror:1 row_mask:0xf bank_mask:0xf
	v_fmac_f32_dpp v239, v27, v167 row_ror:1 row_mask:0xf bank_mask:0xf
	v_fmac_f32_dpp v240, v28, v168 row_ror:1 row_mask:0xf bank_mask:0xf
	v_fmac_f32_dpp v241, v29, v169 row_ror:1 row_mask:0xf bank_mask:0xf
	v_fmac_f32_dpp v212, v14, v170 row_ror:15 row_mask:0xf bank_mask:0xf
	v_fmac_f32_dpp v213, v15, v171 row_ror:15 row_mask:0xf bank_mask:0xf
	v_fmac_f32_dpp v214, v16, v172 row_ror:15 row_mask:0xf bank_mask:0xf
	v_fmac_f32_dpp v215, v17, v173 row_ror:15 row_mask:0xf bank_mask:0xf
	v_fmac_f32_dpp v238, v10, v174 row_ror:15 row_mask:0xf bank_mask:0xf
	v_fmac_f32_dpp v239, v11, v175 row_ror:15 row_mask:0xf bank_mask:0xf
	v_fmac_f32_dpp v240, v12, v176 row_ror:15 row_mask:0xf bank_mask:0xf
	v_fmac_f32_dpp v241, v13, v177 row_ror:15 row_mask:0xf bank_mask:0xf
	v_pk_mul_f32 v[242:243], v[238:239], s[6:7] op_sel_hi:[1,0]
	v_pk_mul_f32 v[244:245], v[240:241], s[6:7] op_sel_hi:[1,0]
	v_exp_f32_e32 v242, v242
	v_exp_f32_e32 v243, v243
	v_exp_f32_e32 v244, v244
	v_exp_f32_e32 v245, v245
	v_add_f32_e32 v242, 1.0, v242
	v_add_f32_e32 v243, 1.0, v243
	v_add_f32_e32 v244, 1.0, v244
	v_add_f32_e32 v245, 1.0, v245
	v_rcp_f32_e32 v242, v242
	v_rcp_f32_e32 v243, v243
	v_rcp_f32_e32 v244, v244
	v_rcp_f32_e32 v245, v245
	s_nop 0
	v_pk_mul_f32 v[242:243], v[238:239], v[242:243]
	v_pk_mul_f32 v[244:245], v[240:241], v[244:245]
	v_pk_mul_f32 v[242:243], v[212:213], v[242:243]
	v_pk_mul_f32 v[244:245], v[214:215], v[244:245]
	v_cvt_pk_bf16_f32 v246, v242, v243
	v_cvt_pk_bf16_f32 v247, v244, v245
	s_add_u32 s26, s94, 0x18c000
	s_addc_u32 s27, s95, 0
	global_store_dwordx2 v217, v[246:247], s[26:27] offset:8
	v_pk_fma_f32 v[212:213], v[146:147], v[14:15], v[102:103]
	v_pk_fma_f32 v[214:215], v[148:149], v[16:17], v[104:105]
	v_pk_fma_f32 v[238:239], v[114:115], v[10:11], v[98:99]
	v_pk_fma_f32 v[240:241], v[116:117], v[12:13], v[100:101]
	v_fmac_f32_dpp v212, v14, v158 row_shr:1 row_mask:0xf bank_mask:0xf
	v_fmac_f32_dpp v213, v15, v159 row_shr:1 row_mask:0xf bank_mask:0xf
	v_fmac_f32_dpp v214, v16, v160 row_shr:1 row_mask:0xf bank_mask:0xf
	v_fmac_f32_dpp v215, v17, v161 row_shr:1 row_mask:0xf bank_mask:0xf
	v_fmac_f32_dpp v238, v10, v154 row_shr:1 row_mask:0xf bank_mask:0xf
	v_fmac_f32_dpp v239, v11, v155 row_shr:1 row_mask:0xf bank_mask:0xf
	v_fmac_f32_dpp v240, v12, v156 row_shr:1 row_mask:0xf bank_mask:0xf
	v_fmac_f32_dpp v241, v13, v157 row_shr:1 row_mask:0xf bank_mask:0xf
	v_fmac_f32_dpp v212, v14, v110 row_shl:1 row_mask:0xf bank_mask:0xf
	v_fmac_f32_dpp v213, v15, v111 row_shl:1 row_mask:0xf bank_mask:0xf
	v_fmac_f32_dpp v214, v16, v112 row_shl:1 row_mask:0xf bank_mask:0xf
	v_fmac_f32_dpp v215, v17, v113 row_shl:1 row_mask:0xf bank_mask:0xf
	v_fmac_f32_dpp v238, v10, v106 row_shl:1 row_mask:0xf bank_mask:0xf
	v_fmac_f32_dpp v239, v11, v107 row_shl:1 row_mask:0xf bank_mask:0xf
	v_fmac_f32_dpp v240, v12, v108 row_shl:1 row_mask:0xf bank_mask:0xf
	v_fmac_f32_dpp v241, v13, v109 row_shl:1 row_mask:0xf bank_mask:0xf
	v_fmac_f32_dpp v212, v22, v162 row_ror:1 row_mask:0xf bank_mask:0xf
	v_fmac_f32_dpp v213, v23, v163 row_ror:1 row_mask:0xf bank_mask:0xf
	v_fmac_f32_dpp v214, v24, v164 row_ror:1 row_mask:0xf bank_mask:0xf
	v_fmac_f32_dpp v215, v25, v165 row_ror:1 row_mask:0xf bank_mask:0xf
	v_fmac_f32_dpp v238, v18, v166 row_ror:1 row_mask:0xf bank_mask:0xf
	v_fmac_f32_dpp v239, v19, v167 row_ror:1 row_mask:0xf bank_mask:0xf
	v_fmac_f32_dpp v240, v20, v168 row_ror:1 row_mask:0xf bank_mask:0xf
	v_fmac_f32_dpp v241, v21, v169 row_ror:1 row_mask:0xf bank_mask:0xf
	v_fmac_f32_dpp v212, v2, v170 row_ror:15 row_mask:0xf bank_mask:0xf
	v_fmac_f32_dpp v213, v3, v171 row_ror:15 row_mask:0xf bank_mask:0xf
	v_fmac_f32_dpp v214, v4, v172 row_ror:15 row_mask:0xf bank_mask:0xf
	v_fmac_f32_dpp v215, v5, v173 row_ror:15 row_mask:0xf bank_mask:0xf
	v_fmac_f32_dpp v238, v6, v174 row_ror:15 row_mask:0xf bank_mask:0xf
	v_fmac_f32_dpp v239, v7, v175 row_ror:15 row_mask:0xf bank_mask:0xf
	v_fmac_f32_dpp v240, v8, v176 row_ror:15 row_mask:0xf bank_mask:0xf
	v_fmac_f32_dpp v241, v9, v177 row_ror:15 row_mask:0xf bank_mask:0xf
	v_pk_mul_f32 v[242:243], v[238:239], s[6:7] op_sel_hi:[1,0]
	v_pk_mul_f32 v[244:245], v[240:241], s[6:7] op_sel_hi:[1,0]
	v_exp_f32_e32 v242, v242
	v_exp_f32_e32 v243, v243
	v_exp_f32_e32 v244, v244
	v_exp_f32_e32 v245, v245
	v_add_f32_e32 v242, 1.0, v242
	v_add_f32_e32 v243, 1.0, v243
	v_add_f32_e32 v244, 1.0, v244
	v_add_f32_e32 v245, 1.0, v245
	v_rcp_f32_e32 v242, v242
	v_rcp_f32_e32 v243, v243
	v_rcp_f32_e32 v244, v244
	v_rcp_f32_e32 v245, v245
	s_nop 0
	v_pk_mul_f32 v[242:243], v[238:239], v[242:243]
	v_pk_mul_f32 v[244:245], v[240:241], v[244:245]
	v_pk_mul_f32 v[242:243], v[212:213], v[242:243]
	v_pk_mul_f32 v[244:245], v[214:215], v[244:245]
	v_cvt_pk_bf16_f32 v246, v242, v243
	v_cvt_pk_bf16_f32 v247, v244, v245
	s_add_u32 s26, s94, 0x1b8000
	s_addc_u32 s27, s95, 0
	global_store_dwordx2 v217, v[246:247], s[26:27] offset:8
	v_pk_fma_f32 v[212:213], v[146:147], v[2:3], v[102:103]
	v_pk_fma_f32 v[214:215], v[148:149], v[4:5], v[104:105]
	v_pk_fma_f32 v[238:239], v[114:115], v[6:7], v[98:99]
	v_pk_fma_f32 v[240:241], v[116:117], v[8:9], v[100:101]
	v_fmac_f32_dpp v212, v2, v158 row_shr:1 row_mask:0xf bank_mask:0xf
	v_fmac_f32_dpp v213, v3, v159 row_shr:1 row_mask:0xf bank_mask:0xf
	v_fmac_f32_dpp v214, v4, v160 row_shr:1 row_mask:0xf bank_mask:0xf
	v_fmac_f32_dpp v215, v5, v161 row_shr:1 row_mask:0xf bank_mask:0xf
	v_fmac_f32_dpp v238, v6, v154 row_shr:1 row_mask:0xf bank_mask:0xf
	v_fmac_f32_dpp v239, v7, v155 row_shr:1 row_mask:0xf bank_mask:0xf
	v_fmac_f32_dpp v240, v8, v156 row_shr:1 row_mask:0xf bank_mask:0xf
	v_fmac_f32_dpp v241, v9, v157 row_shr:1 row_mask:0xf bank_mask:0xf
	v_fmac_f32_dpp v212, v2, v110 row_shl:1 row_mask:0xf bank_mask:0xf
	v_fmac_f32_dpp v213, v3, v111 row_shl:1 row_mask:0xf bank_mask:0xf
	v_fmac_f32_dpp v214, v4, v112 row_shl:1 row_mask:0xf bank_mask:0xf
	v_fmac_f32_dpp v215, v5, v113 row_shl:1 row_mask:0xf bank_mask:0xf
	v_fmac_f32_dpp v238, v6, v106 row_shl:1 row_mask:0xf bank_mask:0xf
	v_fmac_f32_dpp v239, v7, v107 row_shl:1 row_mask:0xf bank_mask:0xf
	v_fmac_f32_dpp v240, v8, v108 row_shl:1 row_mask:0xf bank_mask:0xf
	v_fmac_f32_dpp v241, v9, v109 row_shl:1 row_mask:0xf bank_mask:0xf
	v_fmac_f32_dpp v212, v14, v162 row_ror:1 row_mask:0xf bank_mask:0xf
	v_fmac_f32_dpp v213, v15, v163 row_ror:1 row_mask:0xf bank_mask:0xf
	v_fmac_f32_dpp v214, v16, v164 row_ror:1 row_mask:0xf bank_mask:0xf
	v_fmac_f32_dpp v215, v17, v165 row_ror:1 row_mask:0xf bank_mask:0xf
	v_fmac_f32_dpp v238, v10, v166 row_ror:1 row_mask:0xf bank_mask:0xf
	v_fmac_f32_dpp v239, v11, v167 row_ror:1 row_mask:0xf bank_mask:0xf
	v_fmac_f32_dpp v240, v12, v168 row_ror:1 row_mask:0xf bank_mask:0xf
	v_fmac_f32_dpp v241, v13, v169 row_ror:1 row_mask:0xf bank_mask:0xf
	s_cmp_eq_u32 s4, 64
	s_cbranch_scc1 .Lupc_7
	v_pk_fma_f32 v[212:213], v[188:189], v[170:171], v[212:213]
	v_pk_fma_f32 v[214:215], v[190:191], v[172:173], v[214:215]
	v_pk_fma_f32 v[238:239], v[192:193], v[174:175], v[238:239]
	v_pk_fma_f32 v[240:241], v[194:195], v[176:177], v[240:241]
.Lupc_7:
	s_cmp_lg_u32 s4, 64
	s_cbranch_scc1 .Lupc_8
	s_mov_b64 exec, s[40:41]
	s_lshl_b32 s7, s72, 1
	s_or_b32 s7, s7, 1
	s_mul_i32 s7, s7, 0xb000
	v_readlane_b32 s26, v255, 0
	v_readlane_b32 s27, v255, 1
	s_add_u32 s26, s26, s7
	s_addc_u32 s27, s27, 0
	global_store_dwordx4 v196, v[2:5], s[26:27] offset:16
	s_add_u32 s26, s26, 22528
	s_addc_u32 s27, s27, 0
	global_store_dwordx4 v196, v[6:9], s[26:27] offset:16
	v_readlane_b32 s26, v255, 15
	v_readlane_b32 s27, v255, 16
	s_add_u32 s26, s26, s7
	s_addc_u32 s27, s27, 0
	global_store_dwordx4 v196, v[212:215], s[26:27] offset:16
	s_add_u32 s26, s26, 22528
	s_addc_u32 s27, s27, 0
	global_store_dwordx4 v196, v[238:241], s[26:27] offset:16
	s_mov_b64 exec, -1
.Lupc_8:
	v_pk_mul_f32 v[242:243], v[238:239], s[6:7] op_sel_hi:[1,0]
	v_pk_mul_f32 v[244:245], v[240:241], s[6:7] op_sel_hi:[1,0]
	v_exp_f32_e32 v242, v242
	v_exp_f32_e32 v243, v243
	v_exp_f32_e32 v244, v244
	v_exp_f32_e32 v245, v245
	v_add_f32_e32 v242, 1.0, v242
	v_add_f32_e32 v243, 1.0, v243
	v_add_f32_e32 v244, 1.0, v244
	v_add_f32_e32 v245, 1.0, v245
	v_rcp_f32_e32 v242, v242
	v_rcp_f32_e32 v243, v243
	v_rcp_f32_e32 v244, v244
	v_rcp_f32_e32 v245, v245
	s_nop 0
	v_pk_mul_f32 v[242:243], v[238:239], v[242:243]
	v_pk_mul_f32 v[244:245], v[240:241], v[244:245]
	v_pk_mul_f32 v[242:243], v[212:213], v[242:243]
	v_pk_mul_f32 v[244:245], v[214:215], v[244:245]
	v_cvt_pk_bf16_f32 v246, v242, v243
	v_cvt_pk_bf16_f32 v247, v244, v245
	s_add_u32 s26, s94, 0x1e4000
	s_addc_u32 s27, s95, 0
	global_store_dwordx2 v217, v[246:247], s[26:27] offset:8
	s_andn2_b64 vcc, exec, s[20:21]
	s_mov_b64 s[4:5], -1
	s_cbranch_vccnz .LBB0_179
	v_readlane_b32 s4, v255, 3
	v_readlane_b32 s5, v255, 4
	s_and_b64 vcc, exec, s[4:5]
	s_cbranch_vccnz .LBB0_178
	s_barrier
	s_branch .LBB0_178
